# attention: half-workgroup stagger (2 barriers per key tile: extra one before the exp phase; half 1 runs one segment behind half 0) on top of v42
# baseline (speedup 1.0000x reference)
; #define LAS __attribute__((address_space(3)))
; __device__ __forceinline__ int half_id() { return __builtin_amdgcn_readfirstlane((int)(threadIdx.x >> 8)); }
; __global__ void __launch_bounds__(512, 2) fwd_megakernel(Params p) {
;   cg::grid_group grid = cg::this_grid();
;   if (p.inv_freq[0] < 0.f) grid.sync();
;   volatile LAS unsigned* xst = (volatile LAS unsigned*)(smem_all + 2 * SMEM_BYTES);
;   if (threadIdx.x == 0) { xst[0] = 0u; xst[1] = 0u; xst[2] = 0u; xst[3] = 0u; }
;   __syncthreads();
;   const XcdBarrier xb = xcd_barrier_post((unsigned*)(p.ws + BAR_OFF), xst);
_Z14fwd_megakernel6Params:
	v_readfirstlane_b32 s3, v0
	s_nop 3
	s_and_b32 s3, s3, 0x3ff
	s_lshr_b32 s3, s3, 8
	s_mov_b32 s101, s3
	s_cmp_eq_u32 s3, 0
	s_cbranch_scc1 .Lprio_done
	s_setprio 1

; __device__ __forceinline__ void attn_unit(const WS& ws, int u, bool dry = false) {
;     ...
;     {
;       const u32x4 raw = *(const u32x4*)(ws.QB + (size_t)(b * T_ + qc) * 1536 + hd * 96 + 64 + 8 * lq);
;       u32x4 oth;
;       oth.x = __shfl_xor(raw.x, 32); oth.y = __shfl_xor(raw.y, 32); oth.z = __shfl_xor(raw.z, 32); oth.w = __shfl_xor(raw.w, 32);
;       const float sgn = lq < 2 ? -1.f : 1.f;
;       const float2* rp = ws.ROPE + (size_t)(b * T_ + qc) * 16 + 8 * (lq & 1);
;       const unsigned rw[4] = {raw.x, raw.y, raw.z, raw.w}, ow[4] = {oth.x, oth.y, oth.z, oth.w};
;       unsigned res[4];
; #pragma unroll
;       for (int e = 0; e < 4; ++e) {
;         const float2 c0 = rp[2 * e], c1 = rp[2 * e + 1];
;         const float r0 = bflo(rw[e]) * c0.x + sgn * bflo(ow[e]) * c0.y;
;         const float r1 = bfhi(rw[e]) * c1.x + sgn * bfhi(ow[e]) * c1.y;
;         res[e] = cvt_pk_bf16(r0, r1);
;       }
;       xq[nt][2] = as_bf16x8((u32x4){res[0], res[1], res[2], res[3]});
;     }
;   }
;   float mrun[2] = {-INFINITY, -INFINITY}, lsum[2] = {0.f, 0.f};
;   f32x4 oacc[4][2];
; #pragma unroll
;   for (int a = 0; a < 4; ++a)
; #pragma unroll
;     for (int bb = 0; bb < 2; ++bb) oacc[a][bb] = (f32x4){0.f, 0.f, 0.f, 0.f};
;   u32x4 kregA[3], vregA[2], kregB[3], vregB[2];
;   const bf16_t* vbase = ws.VT + ((size_t)(b * 16 + hd) * 64) * TP_;
;   auto loadg = [&](int kt, u32x4 (&kreg)[3], u32x4 (&vreg)[2]) {
; #pragma unroll
;     for (int i = 0; i < 3; ++i) {
;       const int ci = tid + 256 * i; const int key = ci / 12, ch = ci - key * 12;
;       int gk = 64 * kt + key; if (gk > T_ - 1) gk = T_ - 1;
;       const bf16_t* src = ch < 8 ? ws.KN + (size_t)(b * T_ + gk) * 1024 + hd * 64 + ch * 8
;                                  : ws.KR + (size_t)(b * T_ + gk) * 32 + (ch - 8) * 8;
;       kreg[i] = *(const u32x4*)src;
;     }
; #pragma unroll
;     for (int i = 0; i < 2; ++i) {
;       const int ci = tid + 256 * i; const int dv = ci >> 3, ch = ci & 7;
;       vreg[i] = *(const u32x4*)(vbase + (size_t)dv * TP_ + 64 * kt + ch * 8);
;       if (64 * kt + ch * 8 >= T_) vreg[i] = (u32x4){0u, 0u, 0u, 0u};
;     }
;   };
;   auto stores = [&](int buf, const u32x4 (&kreg)[3], const u32x4 (&vreg)[2]) {
; #pragma unroll
;     for (int i = 0; i < 3; ++i) {
;       const int ci = tid + 256 * i; const int key = ci / 12, ch = ci - key * 12;
.LBB0_862:
	s_or_b64 exec, exec, s[4:5]
	v_cmp_gt_u32_e32 vcc, 2, v109
	v_lshlrev_b32_e32 v122, 16, v22
	v_and_b32_e32 v125, 0xffff0000, v22
	v_cndmask_b32_e64 v107, 1.0, -1.0, vcc
	s_waitcnt lgkmcnt(7)
	v_and_b32_e32 v22, 0xffff0000, v115
	v_mov_b32_e32 v72, v67
	v_mov_b32_e32 v118, v55
	v_lshlrev_b32_e32 v55, 16, v115
	v_mul_f32_e32 v123, v107, v22
	v_mov_b32_e32 v67, v69
	v_mov_b32_e32 v73, v68
	v_mul_f32_e32 v124, v107, v55
	v_pk_mul_f32 v[66:67], v[66:67], v[122:123]
	v_and_b32_e32 v69, 0xffff0000, v23
	v_pk_fma_f32 v[66:67], v[124:125], v[72:73], v[66:67]
	v_mov_b32_e32 v78, v63
	v_cvt_pk_bf16_f32 v22, v66, v67
	v_lshlrev_b32_e32 v66, 16, v23
	s_waitcnt lgkmcnt(6)
	v_and_b32_e32 v23, 0xffff0000, v114
	v_lshlrev_b32_e32 v55, 16, v114
	v_mul_f32_e32 v67, v107, v23
	v_mov_b32_e32 v63, v65
	v_mov_b32_e32 v79, v64
	v_mul_f32_e32 v68, v107, v55
	v_pk_mul_f32 v[62:63], v[62:63], v[66:67]
	s_waitcnt lgkmcnt(5)
	v_lshlrev_b32_e32 v55, 16, v113
	v_pk_fma_f32 v[62:63], v[68:69], v[78:79], v[62:63]
	v_and_b32_e32 v65, 0xffff0000, v24
	v_cvt_pk_bf16_f32 v23, v62, v63
	v_lshlrev_b32_e32 v62, 16, v24
	v_and_b32_e32 v24, 0xffff0000, v113
	v_mul_f32_e32 v64, v107, v55
	v_mul_f32_e32 v63, v107, v24
	v_mov_b32_e32 v55, v57
	v_mov_b32_e32 v119, v56
	v_pk_mul_f32 v[54:55], v[54:55], v[62:63]
	v_and_b32_e32 v57, 0xffff0000, v25
	v_pk_fma_f32 v[54:55], v[64:65], v[118:119], v[54:55]
	s_waitcnt vmcnt(12)
	v_mov_b32_e32 v120, v59
	v_cvt_pk_bf16_f32 v24, v54, v55
	v_lshlrev_b32_e32 v54, 16, v25
	s_waitcnt lgkmcnt(4)
	v_lshlrev_b32_e32 v55, 16, v112
	v_and_b32_e32 v25, 0xffff0000, v112
	v_mul_f32_e32 v56, v107, v55
	v_mul_f32_e32 v55, v107, v25
	v_mov_b32_e32 v59, v61
	v_mov_b32_e32 v121, v60
	v_pk_mul_f32 v[54:55], v[58:59], v[54:55]
	v_lshlrev_b32_e32 v62, 16, v30
	v_pk_fma_f32 v[54:55], v[56:57], v[120:121], v[54:55]
	v_and_b32_e32 v65, 0xffff0000, v30
	s_waitcnt lgkmcnt(3)
	v_and_b32_e32 v30, 0xffff0000, v111
	v_cvt_pk_bf16_f32 v25, v54, v55
	s_waitcnt vmcnt(7)
	v_mov_b32_e32 v54, v47
	v_mov_b32_e32 v60, v35
	v_lshlrev_b32_e32 v35, 16, v111
	v_mul_f32_e32 v63, v107, v30
	v_mov_b32_e32 v47, v49
	v_mov_b32_e32 v55, v48
	v_mul_f32_e32 v64, v107, v35
	v_pk_mul_f32 v[46:47], v[46:47], v[62:63]
	v_and_b32_e32 v49, 0xffff0000, v31
	v_pk_fma_f32 v[46:47], v[64:65], v[54:55], v[46:47]
	v_mov_b32_e32 v56, v43
	v_cvt_pk_bf16_f32 v30, v46, v47
	v_lshlrev_b32_e32 v46, 16, v31
	s_waitcnt lgkmcnt(2)
	v_and_b32_e32 v31, 0xffff0000, v97
	v_lshlrev_b32_e32 v35, 16, v97
	v_mul_f32_e32 v47, v107, v31
	v_mov_b32_e32 v43, v45
	v_mov_b32_e32 v57, v44
	v_mul_f32_e32 v48, v107, v35
	v_pk_mul_f32 v[42:43], v[42:43], v[46:47]
	v_and_b32_e32 v45, 0xffff0000, v32
	v_pk_fma_f32 v[42:43], v[48:49], v[56:57], v[42:43]
	v_mov_b32_e32 v58, v39
	v_cvt_pk_bf16_f32 v31, v42, v43
	v_lshlrev_b32_e32 v42, 16, v32
	s_waitcnt lgkmcnt(1)
	v_and_b32_e32 v32, 0xffff0000, v81
	v_lshlrev_b32_e32 v35, 16, v81
	v_mul_f32_e32 v43, v107, v32
	v_mov_b32_e32 v39, v41
	v_mov_b32_e32 v59, v40
	v_mul_f32_e32 v44, v107, v35
	v_pk_mul_f32 v[38:39], v[38:39], v[42:43]
	s_waitcnt lgkmcnt(0)
	v_lshlrev_b32_e32 v35, 16, v80
	v_pk_fma_f32 v[38:39], v[44:45], v[58:59], v[38:39]
	v_and_b32_e32 v41, 0xffff0000, v33
	v_cvt_pk_bf16_f32 v32, v38, v39
	v_lshlrev_b32_e32 v38, 16, v33
	v_and_b32_e32 v33, 0xffff0000, v80
	global_load_dwordx4 v[42:45], v[70:71], off
	s_nop 0
	global_load_dwordx4 v[70:73], v[148:149], off offset:128
	global_load_dwordx4 v[78:81], v[150:151], off offset:128
	v_mul_f32_e32 v40, v107, v35
	v_mul_f32_e32 v39, v107, v33
	v_mov_b32_e32 v35, v37
	v_mov_b32_e32 v61, v36
	v_pk_mul_f32 v[34:35], v[34:35], v[38:39]
	s_lshr_b32 s4, s8, 8
	v_pk_fma_f32 v[34:35], v[40:41], v[60:61], v[34:35]
	s_movk_i32 s3, 0xd0
	v_lshlrev_b32_e32 v105, 3, v109
	s_mul_i32 s4, s4, 0x12800
	v_cvt_pk_bf16_f32 v33, v34, v35
	v_mul_lo_u32 v34, v171, s3
	v_lshlrev_b32_e32 v35, 4, v96
	v_add3_u32 v177, s4, v34, v35
	v_mul_lo_u32 v34, v172, s3
	v_lshlrev_b32_e32 v35, 4, v100
	v_lshl_or_b32 v38, v105, 1, s4
	v_mul_u32_u24_e32 v39, 0x68, v108
	v_add3_u32 v178, s4, v34, v35
	v_mul_lo_u32 v34, v173, s3
	v_lshlrev_b32_e32 v35, 1, v102
	s_movk_i32 s3, 0x90
	v_lshl_add_u32 v183, v39, 1, v38
	v_xor_b32_e32 v38, 16, v191
	s_lshl_b32 s34, s6, 1
	v_add3_u32 v179, s4, v34, v35
	v_mul_lo_u32 v34, v101, s3
	v_cmp_lt_i32_e32 vcc, v38, v110
	s_min_u32 s5, s34, 31
	v_add3_u32 v180, s4, v34, v104
	v_mul_lo_u32 v34, v116, s3
	v_cndmask_b32_e32 v38, v191, v38, vcc
	s_add_i32 s5, s5, 3
	v_add3_u32 v181, s4, v34, v104
	v_mov_b32_e32 v34, v94
	v_mov_b32_e32 v35, v12
	v_lshlrev_b32_e32 v170, 2, v38
	v_mul_u32_u24_e32 v38, 0x48, v108
	s_and_b32 s36, s5, 62
	v_mov_b32_e32 v36, v98
	v_mov_b32_e32 v37, v12
	v_mov_b32_e32 v107, v12
	v_lshlrev_b32_e32 v182, 2, v109
	v_lshlrev_b32_e32 v38, 1, v38
	v_lshl_add_u64 v[152:153], v[34:35], 1, s[56:57]
	v_lshl_add_u64 v[34:35], v[146:147], 1, s[60:61]
	v_mov_b32_e32 v176, 0
	s_mov_b32 s35, 3
	s_waitcnt vmcnt(9)
	ds_write_b128 v177, v[50:53]
	s_waitcnt vmcnt(8)
	ds_write_b128 v178, v[74:77]
	s_waitcnt vmcnt(7)
	ds_write_b128 v179, v[82:85]
	s_waitcnt vmcnt(6)
	ds_write_b128 v180, v[90:93] offset:26624
	s_add_i32 s37, s36, -1
	v_add3_u32 v184, s4, v38, v105
	v_lshl_add_u64 v[154:155], v[94:95], 1, v[34:35]
	v_lshl_add_u64 v[156:157], v[36:37], 1, s[56:57]
	v_lshl_add_u64 v[158:159], v[98:99], 1, v[34:35]
	v_lshl_add_u64 v[160:161], v[106:107], 1, s[56:57]
	v_lshl_add_u64 v[162:163], v[102:103], 1, v[34:35]
	v_mov_b32_e32 v202, 0xff800000
	v_mov_b32_e32 v185, v182
	v_mov_b32_e32 v201, 0
	v_mov_b32_e32 v203, 0xff800000
	v_mov_b32_e32 v34, 0
	v_mov_b32_e32 v35, v176
	v_mov_b32_e32 v36, v176
	v_mov_b32_e32 v37, v176
	v_mov_b32_e32 v66, 0
	v_mov_b32_e32 v67, v176
	v_mov_b32_e32 v68, v176
	v_mov_b32_e32 v69, v176
	v_mov_b32_e32 v38, 0
	v_mov_b32_e32 v39, v176
	v_mov_b32_e32 v40, v176
	v_mov_b32_e32 v41, v176
	v_mov_b32_e32 v74, 0
	v_mov_b32_e32 v75, v176
	v_mov_b32_e32 v76, v176
	v_mov_b32_e32 v77, v176
	v_mov_b32_e32 v46, 0
	v_mov_b32_e32 v47, v176
	v_mov_b32_e32 v48, v176
	v_mov_b32_e32 v49, v176
	v_mov_b32_e32 v90, 0
	v_mov_b32_e32 v91, v176
	v_mov_b32_e32 v92, v176
	v_mov_b32_e32 v93, v176
	v_mov_b32_e32 v62, 0
	v_mov_b32_e32 v63, v176
	v_mov_b32_e32 v64, v176
	v_mov_b32_e32 v65, v176
	v_mov_b32_e32 v94, 0
	v_mov_b32_e32 v95, v176
	v_mov_b32_e32 v96, v176
	v_mov_b32_e32 v97, v176
	s_waitcnt vmcnt(5)
	ds_write_b128 v181, v[86:89] offset:26624
	s_waitcnt lgkmcnt(0)
	s_barrier
	s_cmp_eq_u32 s101, 0
	s_cbranch_scc1 .Lat_h0
	s_barrier
; #define MFMA16(a, b, c) __builtin_amdgcn_mfma_f32_16x16x32_bf16((a), (b), (c), 0, 0, 0)
; __device__ __forceinline__ void attn_unit(const WS& ws, int u, bool dry = false) {
;     ...
;   auto loadg = [&](int kt, u32x4 (&kreg)[3], u32x4 (&vreg)[2]) {
; #pragma unroll
;     for (int i = 0; i < 3; ++i) {
;       const int ci = tid + 256 * i; const int key = ci / 12, ch = ci - key * 12;
;       int gk = 64 * kt + key; if (gk > T_ - 1) gk = T_ - 1;
;       const bf16_t* src = ch < 8 ? ws.KN + (size_t)(b * T_ + gk) * 1024 + hd * 64 + ch * 8
;                                  : ws.KR + (size_t)(b * T_ + gk) * 32 + (ch - 8) * 8;
;       kreg[i] = *(const u32x4*)src;
;     }
; #pragma unroll
;     for (int i = 0; i < 2; ++i) {
;       const int ci = tid + 256 * i; const int dv = ci >> 3, ch = ci & 7;
;       vreg[i] = *(const u32x4*)(vbase + (size_t)dv * TP_ + 64 * kt + ch * 8);
;       if (64 * kt + ch * 8 >= T_) vreg[i] = (u32x4){0u, 0u, 0u, 0u};
;     }
;     ...
;     { const int kn = kt + 2 < nkt2 ? kt + 2 : nkt2 - 1; loadg(kn, kreg, vreg); }
;     const bf16_t* Kb = Kt + buf * 64 * 104;
;     const bf16_t* Vb = Vl + buf * 64 * 72;
;     f32x4 s[4][2];
; #pragma unroll
;     for (int mt = 0; mt < 4; ++mt) {
;       s[mt][0] = (f32x4){0.f, 0.f, 0.f, 0.f}; s[mt][1] = (f32x4){0.f, 0.f, 0.f, 0.f};
; #pragma unroll
;       for (int ks = 0; ks < 3; ++ks) {
;         const bf16x8 kf = *(const bf16x8*)(Kb + (16 * mt + lr) * 104 + 32 * ks + 8 * lq);
;         s[mt][0] = MFMA16(kf, xq[0][ks], s[mt][0]);
;         s[mt][1] = MFMA16(kf, xq[1][ks], s[mt][1]);
;       }
;     }
.Lat_h0:
.LBB0_863:
	ds_read_b128 v[50:53], v183
	ds_read_b128 v[54:57], v183 offset:64
	s_add_i32 s4, s35, -1
	s_min_i32 s4, s4, s37
	s_lshl_b32 s4, s4, 6
	s_waitcnt lgkmcnt(1)
	v_mfma_f32_16x16x32_bf16 v[58:61], v[50:53], v[0:3], 0
	s_ashr_i32 s5, s4, 31
	s_lshl_b64 s[6:7], s[4:5], 1
	s_add_i32 s5, s35, -3
	v_mfma_f32_16x16x32_bf16 v[50:53], v[50:53], v[14:17], 0
	s_cmp_lt_u32 s5, s34
	s_waitcnt lgkmcnt(0)
	v_mfma_f32_16x16x32_bf16 v[58:61], v[54:57], v[4:7], v[58:61]
	v_mfma_f32_16x16x32_bf16 v[50:53], v[54:57], v[8:11], v[50:53]
	ds_read_b128 v[54:57], v183 offset:128
	ds_read_b128 v[82:85], v183 offset:3328
	s_waitcnt lgkmcnt(1)
	v_mfma_f32_16x16x32_bf16 v[98:101], v[54:57], v[30:33], v[50:53]
	s_nop 3
	ds_read_b128 v[50:53], v183 offset:3392
	v_mfma_f32_16x16x32_bf16 v[114:117], v[54:57], v[22:25], v[58:61]
	s_nop 2
	v_add_u32_e32 v58, s4, v171
	s_waitcnt lgkmcnt(1)
	v_mfma_f32_16x16x32_bf16 v[54:57], v[82:85], v[0:3], 0
	v_min_i32_e32 v86, 0x80f, v58
	v_add_u32_e32 v86, s66, v86
	v_ashrrev_i32_e32 v87, 31, v86
	v_mfma_f32_16x16x32_bf16 v[58:61], v[82:85], v[14:17], 0
	ds_read_b128 v[82:85], v183 offset:3456
	v_lshlrev_b64 v[88:89], 11, v[86:87]
	v_lshlrev_b64 v[86:87], 6, v[86:87]
	s_waitcnt lgkmcnt(1)
	v_mfma_f32_16x16x32_bf16 v[54:57], v[50:53], v[4:7], v[54:57]
	v_lshl_add_u64 v[102:103], v[154:155], 0, v[88:89]
	v_mfma_f32_16x16x32_bf16 v[58:61], v[50:53], v[8:11], v[58:61]
	v_lshl_add_u64 v[50:51], v[152:153], 0, v[86:87]
	ds_read_b128 v[86:89], v183 offset:6656
	v_lshl_add_u64 v[50:51], v[50:51], 0, s[86:87]
	s_waitcnt lgkmcnt(1)
	v_mfma_f32_16x16x32_bf16 v[118:121], v[82:85], v[22:25], v[54:57]
	v_cndmask_b32_e64 v51, v51, v103, s[38:39]
	v_cndmask_b32_e64 v50, v50, v102, s[38:39]
	global_load_dwordx4 v[50:53], v[50:51], off
	v_add_u32_e32 v54, s4, v172
	v_mfma_f32_16x16x32_bf16 v[102:105], v[82:85], v[30:33], v[58:61]
	v_min_i32_e32 v82, 0x80f, v54
	ds_read_b128 v[54:57], v183 offset:6720
	v_add_u32_e32 v106, s66, v82
	s_waitcnt lgkmcnt(1)
	v_mfma_f32_16x16x32_bf16 v[58:61], v[86:89], v[0:3], 0
	v_ashrrev_i32_e32 v107, 31, v106
	v_lshlrev_b64 v[108:109], 11, v[106:107]
	v_lshlrev_b64 v[106:107], 6, v[106:107]
	v_mfma_f32_16x16x32_bf16 v[82:85], v[86:89], v[14:17], 0
	ds_read_b128 v[86:89], v183 offset:6784
	v_lshl_add_u64 v[106:107], v[156:157], 0, v[106:107]
	v_lshl_add_u64 v[108:109], v[158:159], 0, v[108:109]
	v_lshl_add_u64 v[106:107], v[106:107], 0, s[86:87]
	s_waitcnt lgkmcnt(1)
	v_mfma_f32_16x16x32_bf16 v[58:61], v[54:57], v[4:7], v[58:61]
	v_cndmask_b32_e64 v107, v107, v109, s[40:41]
	v_cndmask_b32_e64 v106, v106, v108, s[40:41]
	v_mfma_f32_16x16x32_bf16 v[82:85], v[54:57], v[8:11], v[82:85]
	global_load_dwordx4 v[54:57], v[106:107], off
	ds_read_b128 v[106:109], v183 offset:9984
	s_waitcnt lgkmcnt(1)
	v_mfma_f32_16x16x32_bf16 v[122:125], v[86:89], v[22:25], v[58:61]
	s_nop 2
	v_add_u32_e32 v58, s4, v173
	v_min_i32_e32 v58, 0x80f, v58
	v_mfma_f32_16x16x32_bf16 v[110:113], v[86:89], v[30:33], v[82:85]
	v_add_u32_e32 v126, s66, v58
	v_ashrrev_i32_e32 v127, 31, v126
	v_lshlrev_b64 v[86:87], 11, v[126:127]
	ds_read_b128 v[82:85], v183 offset:10048
	v_lshl_add_u64 v[130:131], v[162:163], 0, v[86:87]
	v_lshlrev_b64 v[86:87], 6, v[126:127]
	s_waitcnt lgkmcnt(1)
	v_mfma_f32_16x16x32_bf16 v[58:61], v[106:109], v[0:3], 0
	v_lshl_add_u64 v[126:127], v[160:161], 0, v[86:87]
	v_lshl_add_u64 v[132:133], v[126:127], 0, s[86:87]
	v_cndmask_b32_e64 v131, v133, v131, s[42:43]
	v_mfma_f32_16x16x32_bf16 v[86:89], v[106:109], v[14:17], 0
	v_cndmask_b32_e64 v130, v132, v130, s[42:43]
	ds_read_b128 v[106:109], v183 offset:10112
	s_waitcnt lgkmcnt(1)
	v_mfma_f32_16x16x32_bf16 v[126:129], v[82:85], v[4:7], v[58:61]
	s_nop 2
	global_load_dwordx4 v[58:61], v[130:131], off
	v_mfma_f32_16x16x32_bf16 v[130:133], v[82:85], v[8:11], v[86:89]
	v_lshl_add_u64 v[82:83], v[148:149], 0, s[6:7]
	v_lshl_add_u64 v[84:85], v[150:151], 0, s[6:7]
	s_nop 0
	global_load_dwordx4 v[86:89], v[82:83], off
	s_nop 0
	global_load_dwordx4 v[82:85], v[84:85], off
	s_waitcnt lgkmcnt(0)
	v_mfma_f32_16x16x32_bf16 v[126:129], v[106:109], v[22:25], v[126:129]
	v_mfma_f32_16x16x32_bf16 v[106:109], v[106:109], v[30:33], v[130:133]
	s_cbranch_scc1 .LBB0_865
; __device__ __forceinline__ void attn_unit(const WS& ws, int u, bool dry = false) {
;     ...
;     if (kt >= 2 * qb) {
; #pragma unroll
;       for (int mt = 0; mt < 4; ++mt)
; #pragma unroll
;         for (int nt = 0; nt < 2; ++nt)
; #pragma unroll
;           for (int jj = 0; jj < 4; ++jj) {
;             const int key = 64 * kt + 16 * mt + 4 * lq + jj;
;             if (key > qi[nt]) s[mt][nt][jj] = -INFINITY;
;           }
;     }
	v_cmp_gt_i32_e32 vcc, v185, v169
	s_nop 0
	v_mov_b32_e32 v130, s17
	v_cmp_lt_i32_e64 s[44:45], v185, v169
	v_cndmask_b32_e32 v130, v114, v130, vcc
	v_add_u32_e32 v131, 2, v185
	v_cndmask_b32_e64 v114, v130, v114, s[44:45]
	v_cndmask_b32_e64 v115, v194, v115, s[44:45]
	v_cmp_le_i32_e64 s[44:45], v131, v169
	v_add_u32_e32 v132, 3, v185
	v_mov_b32_e32 v130, s17
	v_cndmask_b32_e64 v116, v194, v116, s[44:45]
	v_cmp_le_i32_e64 s[44:45], v132, v169
	v_add_u32_e32 v133, 19, v185
	v_add_u32_e32 v134, 35, v185
	v_cndmask_b32_e64 v117, v194, v117, s[44:45]
	v_cmp_gt_i32_e64 s[44:45], v185, v13
	s_nop 1
	v_cndmask_b32_e64 v130, v98, v130, s[44:45]
	v_cmp_lt_i32_e64 s[44:45], v185, v13
	s_nop 1
	v_cndmask_b32_e64 v98, v130, v98, s[44:45]
	v_cndmask_b32_e64 v99, v194, v99, s[44:45]
	v_cmp_le_i32_e64 s[44:45], v131, v13
	v_add_u32_e32 v130, 16, v185
	v_add_u32_e32 v131, 17, v185
	v_cndmask_b32_e64 v100, v194, v100, s[44:45]
	v_cmp_le_i32_e64 s[44:45], v132, v13
	v_add_u32_e32 v132, 18, v185
	s_nop 0
	v_cndmask_b32_e64 v101, v194, v101, s[44:45]
	v_cmp_gt_i32_e64 s[44:45], v130, v169
	v_mov_b32_e32 v130, s17
	v_cndmask_b32_e32 v102, v102, v130, vcc
	v_cmp_le_i32_e32 vcc, v131, v13
	v_cndmask_b32_e64 v118, v118, v130, s[44:45]
	v_cmp_le_i32_e64 s[44:45], v131, v169
	v_cndmask_b32_e32 v103, v194, v103, vcc
	v_cmp_le_i32_e32 vcc, v132, v13
	v_add_u32_e32 v131, 32, v185
	v_cndmask_b32_e64 v119, v194, v119, s[44:45]
	v_cndmask_b32_e32 v104, v194, v104, vcc
	v_cmp_le_i32_e32 vcc, v133, v13
	v_cmp_le_i32_e64 s[44:45], v132, v169
	v_add_u32_e32 v132, 33, v185
	v_cndmask_b32_e32 v105, v194, v105, vcc
	v_cmp_gt_i32_e32 vcc, v131, v169
	v_cndmask_b32_e64 v120, v194, v120, s[44:45]
	v_cmp_le_i32_e64 s[44:45], v133, v169
	v_cndmask_b32_e32 v122, v122, v130, vcc
	v_cmp_le_i32_e32 vcc, v132, v169
	v_add_u32_e32 v133, 34, v185
	v_cndmask_b32_e64 v121, v194, v121, s[44:45]
	v_cndmask_b32_e32 v123, v194, v123, vcc
	v_cmp_le_i32_e32 vcc, v133, v169
	s_nop 1
	v_cndmask_b32_e32 v124, v194, v124, vcc
	v_cmp_le_i32_e32 vcc, v134, v169
	s_nop 1
	v_cndmask_b32_e32 v125, v194, v125, vcc
	v_cmp_gt_i32_e32 vcc, v131, v13
	v_add_u32_e32 v131, 48, v185
	s_nop 0
	v_cndmask_b32_e32 v110, v110, v130, vcc
	v_cmp_le_i32_e32 vcc, v132, v13
	v_add_u32_e32 v132, 49, v185
	s_nop 0
	v_cndmask_b32_e32 v111, v194, v111, vcc
	v_cmp_le_i32_e32 vcc, v133, v13
	v_add_u32_e32 v133, 50, v185
	s_nop 0
	v_cndmask_b32_e32 v112, v194, v112, vcc
	v_cmp_le_i32_e32 vcc, v134, v13
	v_add_u32_e32 v134, 51, v185
	s_nop 0
	v_cndmask_b32_e32 v113, v194, v113, vcc
	v_cmp_gt_i32_e32 vcc, v131, v169
	s_nop 1
	v_cndmask_b32_e32 v126, v126, v130, vcc
	v_cmp_le_i32_e32 vcc, v132, v169
	s_nop 1
	v_cndmask_b32_e32 v127, v194, v127, vcc
	v_cmp_le_i32_e32 vcc, v133, v169
	s_nop 1
	v_cndmask_b32_e32 v128, v194, v128, vcc
	v_cmp_le_i32_e32 vcc, v134, v169
	s_nop 1
	v_cndmask_b32_e32 v129, v194, v129, vcc
	v_cmp_gt_i32_e32 vcc, v131, v13
	s_nop 1
	v_cndmask_b32_e32 v106, v106, v130, vcc
	v_cmp_le_i32_e32 vcc, v132, v13
	s_nop 1
	v_cndmask_b32_e32 v107, v194, v107, vcc
	v_cmp_le_i32_e32 vcc, v133, v13
	s_nop 1
	v_cndmask_b32_e32 v108, v194, v108, vcc
	v_cmp_le_i32_e32 vcc, v134, v13
	s_nop 1
	v_cndmask_b32_e32 v109, v194, v109, vcc

; #define MFMA16(a, b, c) __builtin_amdgcn_mfma_f32_16x16x32_bf16((a), (b), (c), 0, 0, 0)
; __device__ __forceinline__ void attn_unit(const WS& ws, int u, bool dry = false) {
;     ...
;     bf16x8 pf[2][2];
; #pragma unroll
;     for (int nt = 0; nt < 2; ++nt) {
;       float mx = -INFINITY;
; #pragma unroll
;       for (int mt = 0; mt < 4; ++mt) mx = fmaxf(mx, fmaxf(fmaxf(s[mt][nt][0], s[mt][nt][1]), fmaxf(s[mt][nt][2], s[mt][nt][3])));
;       mx = fmaxf(mx, __shfl_xor(mx, 16)); mx = fmaxf(mx, __shfl_xor(mx, 32));
;       if (__builtin_amdgcn_ballot_w64(mx > mrun[nt]) != 0ull) {
;         const float mnew = fmaxf(mrun[nt], mx);
;         const float alpha = __builtin_amdgcn_exp2f(mrun[nt] - mnew);
;         mrun[nt] = mnew;
;         lsum[nt] *= alpha;
; #pragma unroll
;         for (int mt = 0; mt < 4; ++mt) oacc[mt][nt] = scale4(oacc[mt][nt], alpha);
;       }
;       const float mnew = mrun[nt];
;       float ps = 0.f;
; #pragma unroll
;       for (int mt = 0; mt < 4; ++mt)
; #pragma unroll
;         for (int jj = 0; jj < 4; ++jj) { const float pv = __builtin_amdgcn_exp2f(s[mt][nt][jj] - mnew); s[mt][nt][jj] = pv; ps += pv; }
;       lsum[nt] += ps;
; #pragma unroll
;       for (int ks = 0; ks < 2; ++ks) {
;         u32x4 pk;
;         pk.x = cvt_pk_bf16(s[2 * ks][nt][0], s[2 * ks][nt][1]); pk.y = cvt_pk_bf16(s[2 * ks][nt][2], s[2 * ks][nt][3]);
;         pk.z = cvt_pk_bf16(s[2 * ks + 1][nt][0], s[2 * ks + 1][nt][1]); pk.w = cvt_pk_bf16(s[2 * ks + 1][nt][2], s[2 * ks + 1][nt][3]);
;         pf[nt][ks] = as_bf16x8(pk);
;       }
;     }
; #pragma unroll
;     for (int mt = 0; mt < 4; ++mt)
; #pragma unroll
;       for (int ks = 0; ks < 2; ++ks) {
;         const u32x2 lo = *(const u32x2*)(Vb + (16 * mt + lr) * 72 + 32 * ks + 4 * lq);
;         const u32x2 hi = *(const u32x2*)(Vb + (16 * mt + lr) * 72 + 32 * ks + 16 + 4 * lq);
;         const bf16x8 vf = as_bf16x8((u32x4){lo.x, lo.y, hi.x, hi.y});
;         oacc[mt][0] = MFMA16(vf, pf[0][ks], oacc[mt][0]);
;         oacc[mt][1] = MFMA16(vf, pf[1][ks], oacc[mt][1]);
;       }
;     stores(buf ^ 1, kregn, vregn);
;     __syncthreads();
.LBB0_869:
	s_barrier
	v_sub_f32_e32 v98, v98, v202
	v_exp_f32_e32 v208, v98
	v_sub_f32_e32 v98, v99, v202
	v_exp_f32_e32 v209, v98
	v_sub_f32_e32 v98, v100, v202
	v_exp_f32_e32 v210, v98
	v_sub_f32_e32 v98, v101, v202
	v_exp_f32_e32 v211, v98
	v_sub_f32_e32 v98, v102, v202
	v_exp_f32_e32 v212, v98
	v_sub_f32_e32 v98, v103, v202
	v_sub_f32_e32 v114, v114, v203
	v_exp_f32_e32 v213, v98
	v_sub_f32_e32 v98, v104, v202
	v_exp_f32_e32 v227, v114
	v_sub_f32_e32 v114, v115, v203
	v_exp_f32_e32 v214, v98
	v_sub_f32_e32 v98, v105, v202
	v_exp_f32_e32 v228, v114
	v_sub_f32_e32 v114, v116, v203
	v_exp_f32_e32 v215, v98
	v_sub_f32_e32 v98, v110, v202
	v_exp_f32_e32 v229, v114
	v_sub_f32_e32 v114, v117, v203
	v_exp_f32_e32 v216, v98
	v_sub_f32_e32 v98, v111, v202
	v_exp_f32_e32 v230, v114
	v_sub_f32_e32 v114, v118, v203
	v_exp_f32_e32 v205, v98
	v_sub_f32_e32 v98, v112, v202
	v_exp_f32_e32 v231, v114
	v_sub_f32_e32 v114, v119, v203
	v_exp_f32_e32 v206, v98
	v_sub_f32_e32 v98, v113, v202
	v_add_u32_e32 v103, 0x6800, v184
	v_exp_f32_e32 v232, v114
	v_sub_f32_e32 v114, v120, v203
	v_exp_f32_e32 v207, v98
	ds_read2_b64 v[98:101], v103 offset1:4
	v_exp_f32_e32 v233, v114
	v_sub_f32_e32 v114, v121, v203
	v_exp_f32_e32 v234, v114
	v_sub_f32_e32 v114, v122, v203
	v_exp_f32_e32 v235, v114
	v_sub_f32_e32 v114, v123, v203
	v_exp_f32_e32 v204, v114
	v_sub_f32_e32 v114, v124, v203
	v_exp_f32_e32 v221, v114
	v_sub_f32_e32 v114, v125, v203
	v_sub_f32_e32 v102, v106, v202
	v_exp_f32_e32 v223, v114
	v_sub_f32_e32 v114, v126, v203
	v_exp_f32_e32 v219, v102
	v_sub_f32_e32 v102, v107, v202
	ds_read2_b64 v[110:113], v103 offset0:8 offset1:12
	v_exp_f32_e32 v225, v114
	v_sub_f32_e32 v114, v127, v203
	v_exp_f32_e32 v217, v102
	v_sub_f32_e32 v102, v108, v202
	v_exp_f32_e32 v222, v114
	v_sub_f32_e32 v114, v128, v203
	v_cvt_pk_bf16_f32 v118, v227, v228
	v_cvt_pk_bf16_f32 v119, v229, v230
	v_cvt_pk_bf16_f32 v120, v231, v232
	v_cvt_pk_bf16_f32 v121, v233, v234
	v_exp_f32_e32 v218, v102
	v_cvt_pk_bf16_f32 v102, v208, v209
	v_cvt_pk_bf16_f32 v103, v210, v211
	v_cvt_pk_bf16_f32 v104, v212, v213
	v_cvt_pk_bf16_f32 v105, v214, v215
	v_exp_f32_e32 v224, v114
	v_sub_f32_e32 v114, v129, v203
	s_waitcnt lgkmcnt(1)
	v_mfma_f32_16x16x32_bf16 v[94:97], v[98:101], v[118:121], v[94:97]
	v_exp_f32_e32 v226, v114
	v_cvt_pk_bf16_f32 v114, v235, v204
	v_cvt_pk_bf16_f32 v115, v221, v223
	v_mfma_f32_16x16x32_bf16 v[62:65], v[98:101], v[102:105], v[62:65]
	v_sub_f32_e32 v98, v109, v202
	v_exp_f32_e32 v220, v98
	v_cvt_pk_bf16_f32 v116, v225, v222
	v_cvt_pk_bf16_f32 v117, v224, v226
	v_cvt_pk_bf16_f32 v106, v216, v205
	v_cvt_pk_bf16_f32 v107, v206, v207
	v_cvt_pk_bf16_f32 v108, v219, v217
	v_cvt_pk_bf16_f32 v109, v218, v220
	v_add_u32_e32 v98, 0x7000, v184
	s_waitcnt lgkmcnt(0)
	v_mfma_f32_16x16x32_bf16 v[130:133], v[110:113], v[114:117], v[94:97]
	s_min_i32 s6, s35, s37
	s_lshl_b32 s6, s6, 6
	s_ashr_i32 s7, s6, 31
	v_mfma_f32_16x16x32_bf16 v[94:97], v[110:113], v[106:109], v[62:65]
	s_lshl_b64 s[8:9], s[6:7], 1
	s_add_i32 s5, s5, 1
	s_cmp_lt_u32 s5, s34
	ds_read2_b64 v[62:65], v98 offset0:32 offset1:36
	s_waitcnt lgkmcnt(0)
	v_mfma_f32_16x16x32_bf16 v[90:93], v[62:65], v[118:121], v[90:93]
	v_mfma_f32_16x16x32_bf16 v[46:49], v[62:65], v[102:105], v[46:49]
	ds_read2_b64 v[62:65], v98 offset0:40 offset1:44
	v_add_u32_e32 v98, 0x7800, v184
	s_waitcnt lgkmcnt(0)
	v_mfma_f32_16x16x32_bf16 v[134:137], v[62:65], v[114:117], v[90:93]
	v_mfma_f32_16x16x32_bf16 v[90:93], v[62:65], v[106:109], v[46:49]
	s_nop 2
	ds_read2_b64 v[46:49], v98 offset0:64 offset1:68
	s_waitcnt lgkmcnt(0)
	v_mfma_f32_16x16x32_bf16 v[62:65], v[46:49], v[118:121], v[74:77]
	v_mfma_f32_16x16x32_bf16 v[38:41], v[46:49], v[102:105], v[38:41]
	ds_read2_b64 v[46:49], v98 offset0:72 offset1:76
	s_waitcnt lgkmcnt(0)
	v_mfma_f32_16x16x32_bf16 v[138:141], v[46:49], v[114:117], v[62:65]
	s_nop 3
	v_add_u32_e32 v62, 0x8000, v184
	v_mfma_f32_16x16x32_bf16 v[98:101], v[46:49], v[106:109], v[38:41]
	s_nop 2
	ds_read2_b64 v[38:41], v62 offset0:96 offset1:100
	s_waitcnt lgkmcnt(0)
	v_mfma_f32_16x16x32_bf16 v[46:49], v[38:41], v[118:121], v[66:69]
	v_mfma_f32_16x16x32_bf16 v[34:37], v[38:41], v[102:105], v[34:37]
	ds_read2_b64 v[38:41], v62 offset0:104 offset1:108
	s_waitcnt vmcnt(9)
	ds_write_b128 v177, v[18:21] offset:13312
	s_waitcnt vmcnt(8)
	ds_write_b128 v178, v[26:29] offset:13312
	s_waitcnt vmcnt(7)
	ds_write_b128 v179, v[42:45] offset:13312
	s_waitcnt vmcnt(6)
	ds_write_b128 v180, v[70:73] offset:35840
	s_waitcnt vmcnt(5)
	ds_write_b128 v181, v[78:81] offset:35840
	s_waitcnt lgkmcnt(0)
	s_barrier
; #define MFMA16(a, b, c) __builtin_amdgcn_mfma_f32_16x16x32_bf16((a), (b), (c), 0, 0, 0)
; __device__ __forceinline__ void attn_unit(const WS& ws, int u, bool dry = false) {
;     ...
;   auto loadg = [&](int kt, u32x4 (&kreg)[3], u32x4 (&vreg)[2]) {
; #pragma unroll
;     for (int i = 0; i < 3; ++i) {
;       const int ci = tid + 256 * i; const int key = ci / 12, ch = ci - key * 12;
;       int gk = 64 * kt + key; if (gk > T_ - 1) gk = T_ - 1;
;       const bf16_t* src = ch < 8 ? ws.KN + (size_t)(b * T_ + gk) * 1024 + hd * 64 + ch * 8
;                                  : ws.KR + (size_t)(b * T_ + gk) * 32 + (ch - 8) * 8;
;       kreg[i] = *(const u32x4*)src;
;     }
; #pragma unroll
;     for (int i = 0; i < 2; ++i) {
;       const int ci = tid + 256 * i; const int dv = ci >> 3, ch = ci & 7;
;       vreg[i] = *(const u32x4*)(vbase + (size_t)dv * TP_ + 64 * kt + ch * 8);
;       if (64 * kt + ch * 8 >= T_) vreg[i] = (u32x4){0u, 0u, 0u, 0u};
;     }
;     ...
;     { const int kn = kt + 2 < nkt2 ? kt + 2 : nkt2 - 1; loadg(kn, kreg, vreg); }
;     const bf16_t* Kb = Kt + buf * 64 * 104;
;     const bf16_t* Vb = Vl + buf * 64 * 72;
;     f32x4 s[4][2];
; #pragma unroll
;     for (int mt = 0; mt < 4; ++mt) {
;       s[mt][0] = (f32x4){0.f, 0.f, 0.f, 0.f}; s[mt][1] = (f32x4){0.f, 0.f, 0.f, 0.f};
; #pragma unroll
;       for (int ks = 0; ks < 3; ++ks) {
;         const bf16x8 kf = *(const bf16x8*)(Kb + (16 * mt + lr) * 104 + 32 * ks + 8 * lq);
;         s[mt][0] = MFMA16(kf, xq[0][ks], s[mt][0]);
;         s[mt][1] = MFMA16(kf, xq[1][ks], s[mt][1]);
;       }
;     }
	ds_read_b128 v[18:21], v183 offset:13312
	ds_read_b128 v[26:29], v183 offset:13376
	v_mfma_f32_16x16x32_bf16 v[106:109], v[38:41], v[106:109], v[34:37]
	v_add_u32_e32 v42, s6, v171
	v_min_i32_e32 v42, 0x80f, v42
	s_waitcnt lgkmcnt(1)
	v_mfma_f32_16x16x32_bf16 v[34:37], v[18:21], v[0:3], 0
	v_mfma_f32_16x16x32_bf16 v[18:21], v[18:21], v[14:17], 0
	v_mfma_f32_16x16x32_bf16 v[142:145], v[38:41], v[114:117], v[46:49]
	s_waitcnt lgkmcnt(0)
	v_mfma_f32_16x16x32_bf16 v[34:37], v[26:29], v[4:7], v[34:37]
	s_nop 0
	v_add_u32_e32 v46, s66, v42
	v_ashrrev_i32_e32 v47, 31, v46
	v_lshlrev_b64 v[48:49], 11, v[46:47]
	v_mfma_f32_16x16x32_bf16 v[18:21], v[26:29], v[8:11], v[18:21]
	ds_read_b128 v[26:29], v183 offset:13440
	ds_read_b128 v[38:41], v183 offset:16640
	ds_read_b128 v[42:45], v183 offset:16768
	v_lshlrev_b64 v[46:47], 6, v[46:47]
	s_waitcnt lgkmcnt(2)
	v_mfma_f32_16x16x32_bf16 v[126:129], v[26:29], v[22:25], v[34:37]
	v_lshl_add_u64 v[62:63], v[154:155], 0, v[48:49]
	ds_read_b128 v[74:77], v183 offset:23424
	v_mfma_f32_16x16x32_bf16 v[34:37], v[26:29], v[30:33], v[18:21]
	s_nop 2
	ds_read_b128 v[18:21], v183 offset:16704
	s_waitcnt lgkmcnt(3)
	v_mfma_f32_16x16x32_bf16 v[26:29], v[38:41], v[0:3], 0
	v_mfma_f32_16x16x32_bf16 v[38:41], v[38:41], v[14:17], 0
	s_waitcnt lgkmcnt(0)
	v_mfma_f32_16x16x32_bf16 v[26:29], v[18:21], v[4:7], v[26:29]
	v_mfma_f32_16x16x32_bf16 v[38:41], v[18:21], v[8:11], v[38:41]
	v_lshl_add_u64 v[18:19], v[152:153], 0, v[46:47]
	ds_read_b128 v[46:49], v183 offset:19968
	v_lshl_add_u64 v[18:19], v[18:19], 0, s[86:87]
	v_mfma_f32_16x16x32_bf16 v[122:125], v[42:45], v[22:25], v[26:29]
	v_cndmask_b32_e64 v18, v18, v62, s[38:39]
	v_cndmask_b32_e64 v19, v19, v63, s[38:39]
	global_load_dwordx4 v[18:21], v[18:19], off
	v_add_u32_e32 v26, s6, v172
	v_min_i32_e32 v62, 0x80f, v26
	ds_read_b128 v[26:29], v183 offset:20032
	v_add_u32_e32 v62, s66, v62
	v_ashrrev_i32_e32 v63, 31, v62
	v_lshlrev_b64 v[64:65], 11, v[62:63]
	v_lshl_add_u64 v[66:67], v[158:159], 0, v[64:65]
	v_lshlrev_b64 v[68:69], 6, v[62:63]
	ds_read_b128 v[62:65], v183 offset:20096
	v_mfma_f32_16x16x32_bf16 v[38:41], v[42:45], v[30:33], v[38:41]
	v_lshl_add_u64 v[68:69], v[156:157], 0, v[68:69]
	v_lshl_add_u64 v[68:69], v[68:69], 0, s[86:87]
	v_cndmask_b32_e64 v67, v69, v67, s[40:41]
	s_waitcnt lgkmcnt(2)
	v_mfma_f32_16x16x32_bf16 v[42:45], v[46:49], v[0:3], 0
	v_cndmask_b32_e64 v66, v68, v66, s[40:41]
	v_mfma_f32_16x16x32_bf16 v[46:49], v[46:49], v[14:17], 0
	s_waitcnt lgkmcnt(1)
	v_mfma_f32_16x16x32_bf16 v[42:45], v[26:29], v[4:7], v[42:45]
	v_mfma_f32_16x16x32_bf16 v[46:49], v[26:29], v[8:11], v[46:49]
	global_load_dwordx4 v[26:29], v[66:67], off
	ds_read_b128 v[66:69], v183 offset:23296
	s_waitcnt lgkmcnt(1)
	v_mfma_f32_16x16x32_bf16 v[118:121], v[62:65], v[22:25], v[42:45]
	v_mfma_f32_16x16x32_bf16 v[46:49], v[62:65], v[30:33], v[46:49]
	ds_read_b128 v[62:65], v183 offset:23360
	s_nop 0
	v_add_u32_e32 v42, s6, v173
	v_min_i32_e32 v42, 0x80f, v42
	v_add_u32_e32 v70, s66, v42
	s_waitcnt lgkmcnt(1)
	v_mfma_f32_16x16x32_bf16 v[42:45], v[66:69], v[0:3], 0
	v_ashrrev_i32_e32 v71, 31, v70
	v_lshlrev_b64 v[72:73], 11, v[70:71]
	v_lshlrev_b64 v[70:71], 6, v[70:71]
	v_lshl_add_u64 v[70:71], v[160:161], 0, v[70:71]
	v_mfma_f32_16x16x32_bf16 v[66:69], v[66:69], v[14:17], 0
	v_lshl_add_u64 v[78:79], v[162:163], 0, v[72:73]
	v_lshl_add_u64 v[80:81], v[70:71], 0, s[86:87]
	v_cndmask_b32_e64 v79, v81, v79, s[42:43]
	s_waitcnt lgkmcnt(0)
	v_mfma_f32_16x16x32_bf16 v[70:73], v[62:65], v[4:7], v[42:45]
	v_cndmask_b32_e64 v78, v80, v78, s[42:43]
	v_mfma_f32_16x16x32_bf16 v[62:65], v[62:65], v[8:11], v[66:69]
	s_nop 0
	global_load_dwordx4 v[42:45], v[78:79], off
	s_nop 0
	v_lshl_add_u64 v[66:67], v[148:149], 0, s[8:9]
	v_lshl_add_u64 v[68:69], v[150:151], 0, s[8:9]
	v_mfma_f32_16x16x32_bf16 v[114:117], v[74:77], v[22:25], v[70:73]
	s_nop 2
	global_load_dwordx4 v[70:73], v[66:67], off
	global_load_dwordx4 v[78:81], v[68:69], off
	v_mfma_f32_16x16x32_bf16 v[62:65], v[74:77], v[30:33], v[62:65]
	s_cbranch_scc1 .LBB0_871
; __device__ __forceinline__ void attn_unit(const WS& ws, int u, bool dry = false) {
;     ...
;     if (kt >= 2 * qb) {
; #pragma unroll
;       for (int mt = 0; mt < 4; ++mt)
; #pragma unroll
;         for (int nt = 0; nt < 2; ++nt)
; #pragma unroll
;           for (int jj = 0; jj < 4; ++jj) {
;             const int key = 64 * kt + 16 * mt + 4 * lq + jj;
;             if (key > qi[nt]) s[mt][nt][jj] = -INFINITY;
;           }
;     }
	v_add_u32_e32 v67, 64, v185
	v_mov_b32_e32 v66, s17
	v_cmp_gt_i32_e32 vcc, v67, v169
	v_cmp_lt_i32_e64 s[44:45], v67, v169
	v_add_u32_e32 v68, 0x42, v185
	v_cndmask_b32_e32 v66, v126, v66, vcc
	v_cndmask_b32_e64 v126, v66, v126, s[44:45]
	v_cndmask_b32_e64 v127, v194, v127, s[44:45]
	v_cmp_le_i32_e64 s[44:45], v68, v169
	v_add_u32_e32 v69, 0x43, v185
	v_mov_b32_e32 v66, s17
	v_cndmask_b32_e64 v128, v194, v128, s[44:45]
	v_cmp_le_i32_e64 s[44:45], v69, v169
	v_add_u32_e32 v74, 0x63, v185
	s_nop 0
	v_cndmask_b32_e64 v129, v194, v129, s[44:45]
	v_cmp_gt_i32_e64 s[44:45], v67, v13
	s_nop 1
	v_cndmask_b32_e64 v66, v34, v66, s[44:45]
	v_cmp_lt_i32_e64 s[44:45], v67, v13
	v_add_u32_e32 v67, 0x50, v185
	s_nop 0
	v_cndmask_b32_e64 v34, v66, v34, s[44:45]
	v_cndmask_b32_e64 v35, v194, v35, s[44:45]
	v_cmp_le_i32_e64 s[44:45], v68, v13
	v_mov_b32_e32 v66, s17
	v_add_u32_e32 v68, 0x52, v185
	v_cndmask_b32_e64 v36, v194, v36, s[44:45]
	v_cmp_le_i32_e64 s[44:45], v69, v13
	v_cndmask_b32_e32 v38, v38, v66, vcc
	v_add_u32_e32 v69, 0x53, v185
	v_cndmask_b32_e64 v37, v194, v37, s[44:45]
	v_cmp_gt_i32_e64 s[44:45], v67, v169
	v_add_u32_e32 v67, 0x51, v185
	v_cmp_le_i32_e32 vcc, v67, v13
	v_cndmask_b32_e64 v122, v122, v66, s[44:45]
	v_cmp_le_i32_e64 s[44:45], v67, v169
	v_cndmask_b32_e32 v39, v194, v39, vcc
	v_cmp_le_i32_e32 vcc, v68, v13
	v_add_u32_e32 v67, 0x60, v185
	v_cndmask_b32_e64 v123, v194, v123, s[44:45]
	v_cndmask_b32_e32 v40, v194, v40, vcc
	v_cmp_le_i32_e32 vcc, v69, v13
	v_cmp_le_i32_e64 s[44:45], v68, v169
	v_add_u32_e32 v68, 0x61, v185
	v_cndmask_b32_e32 v41, v194, v41, vcc
	v_cmp_gt_i32_e32 vcc, v67, v169
	v_cndmask_b32_e64 v124, v194, v124, s[44:45]
	v_cmp_le_i32_e64 s[44:45], v69, v169
	v_cndmask_b32_e32 v118, v118, v66, vcc
	v_cmp_le_i32_e32 vcc, v68, v169
	v_add_u32_e32 v69, 0x62, v185
	v_cndmask_b32_e64 v125, v194, v125, s[44:45]
	v_cndmask_b32_e32 v119, v194, v119, vcc
	v_cmp_le_i32_e32 vcc, v69, v169
	s_nop 1
	v_cndmask_b32_e32 v120, v194, v120, vcc
	v_cmp_le_i32_e32 vcc, v74, v169
	s_nop 1
	v_cndmask_b32_e32 v121, v194, v121, vcc
	v_cmp_gt_i32_e32 vcc, v67, v13
	v_add_u32_e32 v67, 0x70, v185
	s_nop 0
	v_cndmask_b32_e32 v46, v46, v66, vcc
	v_cmp_le_i32_e32 vcc, v68, v13
	v_add_u32_e32 v68, 0x71, v185
	s_nop 0
	v_cndmask_b32_e32 v47, v194, v47, vcc
	v_cmp_le_i32_e32 vcc, v69, v13
	v_add_u32_e32 v69, 0x72, v185
	s_nop 0
	v_cndmask_b32_e32 v48, v194, v48, vcc
	v_cmp_le_i32_e32 vcc, v74, v13
	v_add_u32_e32 v74, 0x73, v185
	s_nop 0
	v_cndmask_b32_e32 v49, v194, v49, vcc
	v_cmp_gt_i32_e32 vcc, v67, v169
	s_nop 1
	v_cndmask_b32_e32 v114, v114, v66, vcc
	v_cmp_le_i32_e32 vcc, v68, v169
	s_nop 1
	v_cndmask_b32_e32 v115, v194, v115, vcc
	v_cmp_le_i32_e32 vcc, v69, v169
	s_nop 1
	v_cndmask_b32_e32 v116, v194, v116, vcc
	v_cmp_le_i32_e32 vcc, v74, v169
	s_nop 1
	v_cndmask_b32_e32 v117, v194, v117, vcc
	v_cmp_gt_i32_e32 vcc, v67, v13
	s_nop 1
	v_cndmask_b32_e32 v62, v62, v66, vcc
	v_cmp_le_i32_e32 vcc, v68, v13
	s_nop 1
	v_cndmask_b32_e32 v63, v194, v63, vcc
	v_cmp_le_i32_e32 vcc, v69, v13
	s_nop 1
	v_cndmask_b32_e32 v64, v194, v64, vcc
	v_cmp_le_i32_e32 vcc, v74, v13
	s_nop 1
	v_cndmask_b32_e32 v65, v194, v65, vcc

; #define MFMA16(a, b, c) __builtin_amdgcn_mfma_f32_16x16x32_bf16((a), (b), (c), 0, 0, 0)
; __device__ __forceinline__ void attn_unit(const WS& ws, int u, bool dry = false) {
;     ...
;     bf16x8 pf[2][2];
; #pragma unroll
;     for (int nt = 0; nt < 2; ++nt) {
;       float mx = -INFINITY;
; #pragma unroll
;       for (int mt = 0; mt < 4; ++mt) mx = fmaxf(mx, fmaxf(fmaxf(s[mt][nt][0], s[mt][nt][1]), fmaxf(s[mt][nt][2], s[mt][nt][3])));
;       mx = fmaxf(mx, __shfl_xor(mx, 16)); mx = fmaxf(mx, __shfl_xor(mx, 32));
;       if (__builtin_amdgcn_ballot_w64(mx > mrun[nt]) != 0ull) {
;         const float mnew = fmaxf(mrun[nt], mx);
;         const float alpha = __builtin_amdgcn_exp2f(mrun[nt] - mnew);
;         mrun[nt] = mnew;
;         lsum[nt] *= alpha;
; #pragma unroll
;         for (int mt = 0; mt < 4; ++mt) oacc[mt][nt] = scale4(oacc[mt][nt], alpha);
;       }
;       const float mnew = mrun[nt];
;       float ps = 0.f;
; #pragma unroll
;       for (int mt = 0; mt < 4; ++mt)
; #pragma unroll
;         for (int jj = 0; jj < 4; ++jj) { const float pv = __builtin_amdgcn_exp2f(s[mt][nt][jj] - mnew); s[mt][nt][jj] = pv; ps += pv; }
;       lsum[nt] += ps;
; #pragma unroll
;       for (int ks = 0; ks < 2; ++ks) {
;         u32x4 pk;
;         pk.x = cvt_pk_bf16(s[2 * ks][nt][0], s[2 * ks][nt][1]); pk.y = cvt_pk_bf16(s[2 * ks][nt][2], s[2 * ks][nt][3]);
;         pk.z = cvt_pk_bf16(s[2 * ks + 1][nt][0], s[2 * ks + 1][nt][1]); pk.w = cvt_pk_bf16(s[2 * ks + 1][nt][2], s[2 * ks + 1][nt][3]);
;         pf[nt][ks] = as_bf16x8(pk);
;       }
;     }
; #pragma unroll
;     for (int mt = 0; mt < 4; ++mt)
; #pragma unroll
;       for (int ks = 0; ks < 2; ++ks) {
;         const u32x2 lo = *(const u32x2*)(Vb + (16 * mt + lr) * 72 + 32 * ks + 4 * lq);
;         const u32x2 hi = *(const u32x2*)(Vb + (16 * mt + lr) * 72 + 32 * ks + 16 + 4 * lq);
;         const bf16x8 vf = as_bf16x8((u32x4){lo.x, lo.y, hi.x, hi.y});
;         oacc[mt][0] = MFMA16(vf, pf[0][ks], oacc[mt][0]);
;         oacc[mt][1] = MFMA16(vf, pf[1][ks], oacc[mt][1]);
;       }
;     stores(buf ^ 1, kregn, vregn);
;     __syncthreads();
;   };
; #pragma unroll 1
;   for (int kt = 0; kt < nkt2; kt += 2) {
;     body(kt, 0, kregA, vregA, kregB, vregB);
;     body(kt + 1, 1, kregB, vregB, kregA, vregA);
.LBB0_877:
	s_barrier
	v_sub_f32_e32 v90, v126, v204
	v_exp_f32_e32 v90, v90
	v_sub_f32_e32 v92, v127, v204
	v_exp_f32_e32 v92, v92
	v_sub_f32_e32 v93, v128, v204
	v_exp_f32_e32 v93, v93
	v_sub_f32_e32 v94, v129, v204
	v_exp_f32_e32 v94, v94
	v_sub_f32_e32 v95, v122, v204
	v_add_f32_e32 v91, 0, v90
	v_exp_f32_e32 v95, v95
	v_sub_f32_e32 v96, v123, v204
	v_add_f32_e32 v91, v92, v91
	v_exp_f32_e32 v96, v96
	v_sub_f32_e32 v97, v124, v204
	v_add_f32_e32 v91, v93, v91
	v_exp_f32_e32 v97, v97
	v_sub_f32_e32 v98, v125, v204
	v_add_f32_e32 v91, v94, v91
	v_exp_f32_e32 v109, v98
	v_sub_f32_e32 v98, v118, v204
	v_add_f32_e32 v91, v95, v91
	v_exp_f32_e32 v98, v98
	v_sub_f32_e32 v99, v119, v204
	v_add_f32_e32 v91, v96, v91
	v_exp_f32_e32 v99, v99
	v_sub_f32_e32 v100, v120, v204
	v_add_f32_e32 v91, v97, v91
	v_exp_f32_e32 v100, v100
	v_sub_f32_e32 v101, v121, v204
	v_add_f32_e32 v91, v109, v91
	v_exp_f32_e32 v101, v101
	v_sub_f32_e32 v106, v114, v204
	v_sub_f32_e32 v107, v115, v204
	v_sub_f32_e32 v34, v34, v203
	v_add_f32_e32 v91, v98, v91
	v_exp_f32_e32 v106, v106
	v_exp_f32_e32 v107, v107
	v_exp_f32_e32 v34, v34
	v_sub_f32_e32 v35, v35, v203
	v_add_f32_e32 v91, v99, v91
	v_exp_f32_e32 v35, v35
	v_sub_f32_e32 v36, v36, v203
	v_add_f32_e32 v91, v100, v91
	v_exp_f32_e32 v36, v36
	v_sub_f32_e32 v37, v37, v203
	v_add_f32_e32 v91, v101, v91
	v_exp_f32_e32 v37, v37
	v_sub_f32_e32 v38, v38, v203
	v_add_f32_e32 v91, v106, v91
	v_cvt_pk_bf16_f32 v98, v98, v99
	v_cvt_pk_bf16_f32 v99, v100, v101
	v_cvt_pk_bf16_f32 v100, v106, v107
	v_cvt_pk_bf16_f32 v106, v90, v92
	v_add_f32_e32 v90, 0, v34
	v_exp_f32_e32 v38, v38
	v_sub_f32_e32 v39, v39, v203
	v_add_f32_e32 v90, v35, v90
	v_exp_f32_e32 v39, v39
	v_sub_f32_e32 v40, v40, v203
	v_add_f32_e32 v90, v36, v90
	v_exp_f32_e32 v40, v40
	v_sub_f32_e32 v41, v41, v203
	v_add_f32_e32 v90, v37, v90
	v_exp_f32_e32 v41, v41
	v_sub_f32_e32 v46, v46, v203
	v_add_f32_e32 v90, v38, v90
	v_exp_f32_e32 v46, v46
	v_sub_f32_e32 v47, v47, v203
	v_add_f32_e32 v90, v39, v90
	v_exp_f32_e32 v47, v47
	v_sub_f32_e32 v48, v48, v203
	v_add_f32_e32 v90, v40, v90
	v_exp_f32_e32 v48, v48
	v_sub_f32_e32 v49, v49, v203
	v_add_f32_e32 v90, v41, v90
	v_exp_f32_e32 v49, v49
	v_sub_f32_e32 v62, v62, v203
	v_sub_f32_e32 v63, v63, v203
	v_add_f32_e32 v90, v46, v90
	v_exp_f32_e32 v62, v62
	v_exp_f32_e32 v63, v63
	v_add_f32_e32 v90, v47, v90
	v_add_f32_e32 v90, v48, v90
	v_add_f32_e32 v90, v49, v90
	v_sub_f32_e32 v64, v64, v203
	v_add_f32_e32 v90, v62, v90
	v_exp_f32_e32 v64, v64
	v_sub_f32_e32 v65, v65, v203
	v_cvt_pk_bf16_f32 v115, v36, v37
	v_cvt_pk_bf16_f32 v36, v62, v63
	v_add_u32_e32 v62, 0x8800, v184
	v_sub_f32_e32 v108, v116, v204
	v_sub_f32_e32 v114, v117, v204
	v_exp_f32_e32 v65, v65
	v_cvt_pk_bf16_f32 v116, v38, v39
	v_cvt_pk_bf16_f32 v117, v40, v41
	ds_read2_b64 v[38:41], v62 offset0:128 offset1:132
	v_add_f32_e32 v90, v63, v90
	v_exp_f32_e32 v108, v108
	v_add_f32_e32 v90, v64, v90
	v_exp_f32_e32 v114, v114
	v_add_f32_e32 v90, v65, v90
	v_cvt_pk_bf16_f32 v37, v64, v65
	ds_read2_b64 v[62:65], v62 offset0:136 offset1:140
	v_add_f32_e32 v91, v107, v91
	v_add_f32_e32 v91, v108, v91
	v_add_f32_e32 v91, v114, v91
	v_cvt_pk_bf16_f32 v101, v108, v114
	v_cvt_pk_bf16_f32 v107, v93, v94
	v_cvt_pk_bf16_f32 v108, v95, v96
	v_cvt_pk_bf16_f32 v109, v97, v109
	v_cvt_pk_bf16_f32 v114, v34, v35
	v_cvt_pk_bf16_f32 v34, v46, v47
	v_cvt_pk_bf16_f32 v35, v48, v49
	s_waitcnt lgkmcnt(1)
	v_mfma_f32_16x16x32_bf16 v[46:49], v[38:41], v[106:109], v[110:113]
	v_add_f32_e32 v176, v176, v90
	v_add_u32_e32 v90, 0x9000, v184
	v_add_f32_e32 v201, v201, v91
	v_mfma_f32_16x16x32_bf16 v[38:41], v[38:41], v[114:117], v[142:145]
	v_or_b32_e32 v91, s6, v174
	v_cmp_lt_i32_e32 vcc, s16, v91
	v_or_b32_e32 v91, s4, v174
	s_waitcnt lgkmcnt(0)
	v_mfma_f32_16x16x32_bf16 v[94:97], v[62:65], v[98:101], v[46:49]
	s_waitcnt vmcnt(1)
	v_cndmask_b32_e64 v73, v73, 0, vcc
	v_cndmask_b32_e64 v72, v72, 0, vcc
	v_cndmask_b32_e64 v71, v71, 0, vcc
	v_mfma_f32_16x16x32_bf16 v[62:65], v[62:65], v[34:37], v[38:41]
	v_cndmask_b32_e64 v70, v70, 0, vcc
	s_waitcnt vmcnt(0)
	v_cndmask_b32_e64 v81, v81, 0, vcc
	v_cndmask_b32_e64 v80, v80, 0, vcc
	ds_read2_b64 v[38:41], v90 offset0:160 offset1:164
	s_waitcnt lgkmcnt(0)
	v_mfma_f32_16x16x32_bf16 v[46:49], v[38:41], v[106:109], v[102:105]
	s_nop 2
	ds_read2_b64 v[102:105], v90 offset0:168 offset1:172
	v_cndmask_b32_e64 v79, v79, 0, vcc
	v_cndmask_b32_e64 v78, v78, 0, vcc
	v_mfma_f32_16x16x32_bf16 v[38:41], v[38:41], v[114:117], v[138:141]
	v_cmp_lt_i32_e32 vcc, s16, v91
	v_add_u32_e32 v110, 0xa000, v184
	s_add_i32 s35, s35, 2
	s_waitcnt lgkmcnt(0)
	v_mfma_f32_16x16x32_bf16 v[90:93], v[102:105], v[98:101], v[46:49]
	s_add_i32 s5, s5, 1
	v_add_u32_e32 v185, 0x80, v185
	s_cmp_ge_u32 s5, s36
	v_mfma_f32_16x16x32_bf16 v[46:49], v[102:105], v[34:37], v[38:41]
	v_add_u32_e32 v102, 0x9800, v184
	v_cndmask_b32_e64 v89, v89, 0, vcc
	v_cndmask_b32_e64 v88, v88, 0, vcc
	ds_read2_b64 v[38:41], v102 offset0:192 offset1:196
	ds_read2_b64 v[102:105], v102 offset0:200 offset1:204
	s_waitcnt lgkmcnt(1)
	v_mfma_f32_16x16x32_bf16 v[74:77], v[38:41], v[106:109], v[74:77]
	v_cndmask_b32_e64 v87, v87, 0, vcc
	v_cndmask_b32_e64 v86, v86, 0, vcc
	v_cndmask_b32_e64 v85, v85, 0, vcc
	v_mfma_f32_16x16x32_bf16 v[38:41], v[38:41], v[114:117], v[134:137]
	v_cndmask_b32_e64 v84, v84, 0, vcc
	v_cndmask_b32_e64 v83, v83, 0, vcc
	v_cndmask_b32_e64 v82, v82, 0, vcc
	s_waitcnt lgkmcnt(0)
	v_mfma_f32_16x16x32_bf16 v[74:77], v[102:105], v[98:101], v[74:77]
	v_mfma_f32_16x16x32_bf16 v[38:41], v[102:105], v[34:37], v[38:41]
	ds_read2_b64 v[102:105], v110 offset0:224 offset1:228
	s_waitcnt lgkmcnt(0)
	v_mfma_f32_16x16x32_bf16 v[66:69], v[102:105], v[106:109], v[66:69]
	ds_read2_b64 v[106:109], v110 offset0:232 offset1:236
	ds_write_b128 v177, v[50:53]
	ds_write_b128 v178, v[54:57]
	ds_write_b128 v179, v[58:61]
	ds_write_b128 v180, v[86:89] offset:26624
	ds_write_b128 v181, v[82:85] offset:26624
	s_waitcnt lgkmcnt(0)
	v_mfma_f32_16x16x32_bf16 v[102:105], v[102:105], v[114:117], v[130:133]
	s_barrier
	v_mfma_f32_16x16x32_bf16 v[66:69], v[106:109], v[98:101], v[66:69]
	v_mfma_f32_16x16x32_bf16 v[34:37], v[106:109], v[34:37], v[102:105]
	s_cbranch_scc1 .LBB0_881
	v_mov_b32_e32 v202, v203
	v_mov_b32_e32 v203, v204
	s_branch .LBB0_863

; __device__ __forceinline__ void attn_unit(const WS& ws, int u, bool dry = false) {
;     ...
; #pragma unroll 1
;   for (int kt = 0; kt < nkt2; kt += 2) {
;     body(kt, 0, kregA, vregA, kregB, vregB);
;     body(kt + 1, 1, kregB, vregB, kregA, vregA);
;   }
; #pragma unroll
;   for (int nt = 0; nt < 2; ++nt) {
.LBB0_881:
	s_cmp_lg_u32 s101, 0
	s_cbranch_scc1 .Lat_e1
	s_barrier
